# w_ffn2_out transposes (86 items) moved from the mixer queue into the idle tail of the phase-1 GEMM queue; GLA loop pinned at its better code placement
# baseline (speedup 1.0000x reference)
; __device__ __forceinline__ void phase_mixer(const Params& p, unsigned char* sm, const int TIDX, const int BIDX, const int rep) {
;     ...
;     for (;;) {
;         __syncthreads();
;         if (TIDX == 0) *sitem = (int)atomicAdd(ctr, 1u);
;         __syncthreads();
;         int it = __builtin_amdgcn_readfirstlane(*sitem);
;         int tl = TIDX; asm volatile("" : "+v"(tl));
;         if (it >= 1760 + 258) break;
;         if (it >= 1760) { if (rep == 0) { int tl2 = TIDX; asm volatile("" : "+v"(tl2)); conv_item(p, sm, 1, it - 1760, tl2); } continue; }
.LBB0_46:
	s_or_b64 exec, exec, s[6:7]
	v_mov_b32_e32 v0, s83
	s_waitcnt lgkmcnt(0)
	s_barrier
	ds_read_b32 v0, v0
	v_mov_b32_e32 v116, v199
	s_mov_b64 s[6:7], -1
	s_waitcnt lgkmcnt(0)
	v_readfirstlane_b32 s44, v0
	s_cmpk_gt_i32 s44, 0x78b
	s_cbranch_scc1 .LBB0_41
	s_cmpk_lt_u32 s44, 0x4a0
	s_cbranch_scc1 .Lq_keep
	s_cmpk_lt_u32 s44, 0x54c
	s_cbranch_scc1 .Lq_conv
	s_sub_i32 s44, s44, 172
	s_branch .Lq_keep

; #define BAR_LDS() do { asm volatile("s_waitcnt lgkmcnt(0)" ::: "memory"); __builtin_amdgcn_s_barrier(); asm volatile("" ::: "memory"); } while (0)
; __device__ __forceinline__ void gla_item(const Params& p, unsigned char* sm, int h, int job0, int jobstride, int nchunks, int tok0, int nvalid, const float* s_init, float* s_out, const int TIDX) {
;     const int tid = TIDX, w = __builtin_amdgcn_readfirstlane(tid >> 6), lane = tid & 63, r16 = lane & 15, g = lane >> 4;
;     unsigned char* QEl = sm; unsigned char* KEl = sm + 17408; unsigned char* KLl = sm + 34816; unsigned char* VTl = sm + 53248; unsigned char* AMl = sm + 90112;
;     float* EBl = (float*)(sm + 99328); float* SSQ = (float*)(sm + 99840); float* RSl = (float*)(sm + 101888); unsigned char* OTl = sm + 102400; float* GNl = (float*)(sm + 136192);
;     const bf16_t* QEg = (const bf16_t*)(p.ws + WS_QE); const bf16_t* KEg = (const bf16_t*)(p.ws + WS_KE); const bf16_t* KLg = (const bf16_t*)(p.ws + WS_KLT);
;     const bf16_t* VTg = (const bf16_t*)(p.ws + WS_VTG); const float* EBg = (const float*)(p.ws + WS_EBL); const bf16_t* GRg = (const bf16_t*)(p.ws + WS_GR);
;     bf16_t* CAT = (bf16_t*)(p.ws + WS_ABUF);
;     f32x4 S[8][2];
; #pragma unroll
;     for (int db = 0; db < 8; ++db) { S[db][0] = (f32x4){0.f, 0.f, 0.f, 0.f}; S[db][1] = (f32x4){0.f, 0.f, 0.f, 0.f}; }
;     if (s_init) {
;         const float* sp = s_init + (size_t)(4 * g) * 256 + 32 * w + r16;
; #pragma unroll
;         for (int db = 0; db < 8; ++db) {
; #pragma unroll
;             for (int j = 0; j < 4; ++j) { S[db][0][j] = sp[j * 256]; S[db][1][j] = sp[j * 256 + 16]; }
;             sp += 16 * 256; asm volatile("" : "+v"(sp));
;         }
;     }
;     u32x4 pq[2], pk[2], pl[2], pv[4]; f32x4 pe;
;     ...
;     BAR_LDS();
;     GLA_LOAD(job0, tok0);
;     GLA_STORE();
;     if (tid < 64) *(f32x4*)(GNl + tid * 4) = *(const f32x4*)(p.in[16] + tid * 4);
;     BAR_LDS();
;     for (int ci = 0; ci < nchunks; ++ci) {
.LBB0_124:
	s_or_b64 exec, exec, s[10:11]
	s_ashr_i32 s10, s12, 3
	s_and_b32 s10, s10, -16
	v_lshlrev_b32_e32 v124, 2, v117
	v_or_b32_e32 v0, s10, v118
	v_or_b32_e32 v125, s10, v124
	v_readlane_b32 s10, v255, 55
	v_readlane_b32 s11, v255, 56
	s_lshl_b32 s90, s13, 5
	s_lshl_b32 s13, s16, 9
	v_lshl_add_u64 v[180:181], v[114:115], 2, s[10:11]
	v_readlane_b32 s10, v255, 41
	s_add_u32 s10, s10, s13
	v_readlane_b32 s11, v255, 42
	s_addc_u32 s11, s11, 0
	s_andn2_b32 s12, s12, 63
	v_mul_lo_u32 v0, v0, s74
	s_lshl_b32 s14, s12, 2
	v_readlane_b32 s15, v254, 10
	v_add_u32_e32 v121, 0, v0
	v_lshlrev_b32_e32 v0, 3, v117
	s_add_i32 s83, s15, s14
	v_readlane_b32 s14, v254, 12
	v_add_u32_e32 v126, 0, v0
	v_readlane_b32 s38, v254, 11
	s_add_i32 s12, s14, s12
	v_add_u32_e32 v210, v126, v0
	v_and_b32_e32 v0, 0xf8, v112
	v_add_u32_e32 v211, s15, v114
	v_add_u32_e32 v212, s38, v114
	v_lshl_add_u32 v112, v118, 1, s12
	v_and_b32_e32 v114, 31, v116
	s_add_i32 s12, 0, 0x21400
	v_lshl_add_u32 v213, v114, 5, s12
	v_readlane_b32 s12, v255, 36
	v_lshlrev_b32_e32 v0, 1, v0
	s_add_u32 s12, s12, s13
	v_readlane_b32 s13, v255, 43
	v_lshl_add_u64 v[182:183], s[10:11], 0, v[0:1]
	v_lshlrev_b32_e32 v0, 4, v114
	s_addc_u32 s13, s13, 0
	v_and_or_b32 v122, s90, 32, v118
	v_readlane_b32 s20, v254, 9
	v_add_u32_e32 v128, s14, v0
	v_lshl_add_u64 v[184:185], s[12:13], 0, v[0:1]
	v_or_b32_e32 v0, 1, v125
	v_or_b32_e32 v130, 2, v125
	v_or_b32_e32 v131, 3, v125
	v_lshlrev_b32_e32 v209, 4, v117
	v_mad_u32_u24 v123, v122, s74, 0
	v_or_b32_e32 v127, s90, v118
	v_lshl_add_u32 v114, v122, 1, s20
	v_cmp_gt_i32_e64 s[12:13], v122, v125
	s_movk_i32 s28, 0x90
	v_cmp_gt_i32_e64 s[14:15], v122, v0
	v_cmp_gt_i32_e64 s[16:17], v122, v130
	v_cmp_gt_i32_e64 s[18:19], v122, v131
	v_or_b32_e32 v122, 16, v122
	v_ashrrev_i32_e32 v116, 5, v116
	v_ashrrev_i32_e32 v113, 5, v113
	v_ashrrev_i32_e32 v119, 5, v119
	v_ashrrev_i32_e32 v120, 5, v120
	v_or_b32_e32 v124, 1, v124
	s_waitcnt lgkmcnt(0)
	s_barrier
	v_add_u32_e32 v115, s20, v209
	v_mul_lo_u32 v129, v125, s28
	v_lshl_add_u32 v132, v122, 1, s20
	v_cmp_gt_i32_e64 s[20:21], v122, v125
	v_mul_lo_u32 v125, v127, s28
	v_cmp_gt_i32_e64 s[28:29], s36, v116
	v_cmp_gt_i32_e64 s[30:31], s36, v113
	v_cmp_gt_i32_e64 s[34:35], s36, v119
	v_cmp_gt_i32_e64 s[36:37], s36, v120
	v_add_u32_e32 v214, s38, v209
	v_lshl_add_u32 v215, v124, 2, s38
	s_movk_i32 s38, 0x210
	v_cmp_eq_u32_e64 s[10:11], 0, v118
	v_cmp_gt_i32_e64 s[22:23], v122, v0
	v_cmp_gt_i32_e64 s[24:25], v122, v130
	v_cmp_gt_i32_e64 s[26:27], v122, v131
	v_mul_u32_u24_e32 v122, 0x110, v118
	v_mul_u32_u24_e32 v0, 0x90, v118
	v_cndmask_b32_e64 v118, 0, v116, s[28:29]
	v_cndmask_b32_e64 v127, 0, v113, s[30:31]
	v_cndmask_b32_e64 v130, 0, v119, s[34:35]
	v_cndmask_b32_e64 v131, 0, v120, s[36:37]
	v_mul_u32_u24_e32 v117, 0x840, v117
	v_mul_u32_u24_e32 v124, 0x210, v124
	v_mul_lo_u32 v133, v116, s38
	v_mul_lo_u32 v134, v113, s38
	v_mul_lo_u32 v135, v119, s38
	v_mul_lo_u32 v136, v120, s38
	s_mov_b32 s91, 1
	s_mov_b32 s81, 0
	s_add_i32 s96, s96, 4
	s_lshl_b32 s84, s45, 6
	v_add_u32_e32 v216, s98, v116
	v_add_u32_e32 v217, s98, v113
	v_add_u32_e32 v218, s98, v119
	v_add_u32_e32 v219, s98, v120
	v_add_u32_e32 v220, s98, v131
	v_add_u32_e32 v221, s98, v130
	v_add_u32_e32 v222, s98, v127
	v_add_u32_e32 v223, s98, v118
	v_add_u32_e32 v224, v121, v209
	v_add_u32_e32 v225, v123, v209
	v_add_u32_e32 v226, v114, v129
	v_add_u32_e32 v227, v132, v129
	v_add_u32_e32 v228, v126, v122
	v_add_u32_e32 v229, v210, v125
	v_add_u32_e32 v230, v115, v0
	v_add_u32_e32 v231, v112, v117
	v_add_u32_e32 v232, v112, v124
	v_add_u32_e32 v233, v128, v133
	v_add_u32_e32 v234, v128, v134
	v_add_u32_e32 v235, v128, v135
	v_add_u32_e32 v236, v128, v136
	s_branch .LBB0_127
	s_nop 0
	s_nop 0
	s_nop 0
	s_nop 0
	s_nop 0
	s_nop 0
	s_nop 0
	s_nop 0
	s_nop 0
	s_nop 0
	s_nop 0
	s_nop 0
.Lgla_next:
	s_add_i32 s96, s96, 4
	s_add_i32 s81, s81, 64
	s_add_i32 s91, s91, 1
	s_cmp_lg_u32 s84, s81
	s_cbranch_scc0 .LBB0_176

; __device__ __forceinline__ void conv_item(const Params& p, unsigned char* sm, int list, int j, const int TIDX) {
;     ...
;     if (list == 0) {
;         if (j < 86) tr_matrix(p.in[11], DFF, DM, (bf16_t*)(p.ws + WS_WFO), DM / 32, 0, nullptr, scr, j * 64 + wid, j * 64 + 64, 8, lane);
; __device__ __forceinline__ void conv_queue(const Params& p, unsigned char* sm, int list, int nitems, unsigned* ctr, const int TIDX) {
;     int* sitem = (int*)(sm + LDS_BYTES - 16);
;     for (;;) {
;         __syncthreads();
;         if (TIDX == 0) *sitem = (int)atomicAdd(ctr, 1u);
;         __syncthreads();
;         const int j = __builtin_amdgcn_readfirstlane(*sitem);
;         if (j >= nitems) break;
;         int tl = TIDX; asm volatile("" : "+v"(tl));
;         conv_item(p, sm, list, j, tl);
.LBB0_409:
	s_or_b64 exec, exec, s[12:13]
	v_mov_b32_e32 v0, s83
	s_waitcnt lgkmcnt(0)
	s_barrier
	ds_read_b32 v0, v0
	s_mov_b64 s[12:13], -1
	s_waitcnt lgkmcnt(0)
	v_readfirstlane_b32 s0, v0
	s_cmpk_gt_i32 s0, 0x123
	s_cbranch_scc1 .LBB0_404
	s_add_u32 s10, s54, 0x2b04000
	s_addc_u32 s11, s55, 0
	v_readlane_b32 s62, v255, 0
	v_readlane_b32 s63, v255, 1
	s_cmpk_lt_i32 s0, 0xce
	s_cbranch_scc1 .Lconv_keep
	s_sub_i32 s0, s0, 206
	s_add_u32 s10, s54, 0x1fce4000
	s_addc_u32 s11, s55, 0
	v_readlane_b32 s62, v255, 28
	v_readlane_b32 s63, v255, 29
.Lconv_keep:
	s_nop 3
	v_mov_b32_e32 v31, v199
	s_cmpk_gt_i32 s0, 0x55
	v_ashrrev_i32_e32 v28, 6, v31
	v_mul_lo_u32 v8, v28, s84
	v_and_b32_e32 v30, 63, v31
	v_add_u32_e32 v29, 0, v8
	s_cbranch_scc0 .LBB0_427
	s_lshl_b32 s3, s0, 6
	s_cmpk_gt_u32 s0, 0xad
	s_cbranch_scc0 .LBB0_416
	s_add_i32 s12, s3, 0xffffd480
	v_add_u32_e32 v9, s12, v28
	s_add_i32 s16, s3, 0xffffd4c0
	v_cmp_gt_i32_e32 vcc, s16, v9
	s_and_saveexec_b64 s[12:13], vcc
	s_cbranch_execz .LBB0_415
	v_lshlrev_b32_e32 v0, 3, v30
	v_and_b32_e32 v0, 56, v0
	v_lshrrev_b32_e32 v5, 3, v30
	v_mul_u32_u24_e32 v6, 0x84, v0
	v_lshlrev_b32_e32 v0, 1, v0
	v_lshrrev_b32_e32 v10, 5, v30
	v_and_b32_e32 v4, 31, v31
	v_lshl_add_u64 v[2:3], s[6:7], 0, v[0:1]
	v_lshlrev_b32_e32 v0, 2, v5
	v_add3_u32 v11, v29, v6, v0
	v_mul_u32_u24_e32 v0, 0x84, v10
	v_lshlrev_b32_e32 v6, 2, v4
	s_lshl_b32 s14, s0, 11
	v_add3_u32 v12, v29, v0, v6
	v_lshlrev_b32_e32 v13, 5, v28
	v_or_b32_e32 v14, s14, v5
	s_add_i32 s17, s14, 0xfffa9000
	s_mov_b64 s[14:15], 0
	v_lshlrev_b32_e32 v0, 2, v4
